# LRU scan loops: next-group x/y loads no longer waited right after issue; conversion deferred to loop end (fresh dest regs)
# speedup vs baseline: 1.0040x; 1.0040x over previous
; __device__ __forceinline__ float bf2f(u16 h) { return __uint_as_float(((uint32_t)h) << 16); }
; __device__ __forceinline__ float sigmoidf_(float x) { return __builtin_amdgcn_rcpf(1.f + __expf(-x)); }
; template <bool FINAL>
; __device__ __forceinline__ void lru_job(const Params& P, int j, int b, int chunk, int h, char* ldsw) {
;     ...
;     for (int tg = 0; tg < 32; tg += 4) {
;       if (tg + 4 < 32) {
; #pragma unroll
;         for (int q = 0; q < 4; ++q) {
;           xqn[q] = bf2f(xs[(size_t)(tg + 4 + q) * 1536]);
;           yqn[q] = FINAL ? bf2f(Z[(rowb + tg + 4 + q) * 1536 + 512 + ch]) : 0.f;
;         }
;       }
; #pragma unroll
;       for (int q = 0; q < 4; ++q) {
;         const int tt = tg + q;
;         const float xt = xq[q];
;         float xcv = cb + v0 * cw0 + v1 * cw1 + v2 * cw2 + xt * cw3;
;         v0 = v1; v1 = v2; v2 = xt;
;         float rr = sigmoidf_(rbuf[tt * 64 + lane] + ba);
;         float ii = sigmoidf_(ibuf[tt * 64 + lane] + bx);
;         float la = -8.f * rr * sp;
;         float a = __expf(la);
;         const float x2 = 2.f * la;
;         const float om = (x2 > -0.03f) ? -x2 * (1.f + x2 * (0.5f + x2 * (0.16666667f + x2 * 0.041666667f))) : 1.f - a * a;
;         float bc = __builtin_amdgcn_sqrtf(om);
;         hst = a * hst + bc * ii * xcv;
;         if (FINAL) {
;           Y[(rowb + tt) * 1024 + ch] = f2bf(hst * gelu_tanh(yq[q]));
;         } else {
;           Ap *= a;
;         }
;       }
.LBB0_475:
	s_add_i32 s64, s64, 4
	s_cmp_gt_u32 s64, 27
	s_cselect_b64 s[72:73], -1, 0
	s_and_b64 vcc, exec, s[72:73]
	s_cbranch_vccnz .LBB0_477
	v_lshl_add_u64 v[4:5], s[54:55], 0, v[106:107]
	global_load_ushort v153, v[4:5], off
	v_lshl_add_u64 v[4:5], s[8:9], 0, v[106:107]
	global_load_ushort v154, v[4:5], off
	v_lshl_add_u64 v[4:5], s[60:61], 0, v[106:107]
	v_lshl_add_u64 v[6:7], s[10:11], 0, v[106:107]
	global_load_ushort v12, v[4:5], off offset:-3072
	global_load_ushort v13, v[4:5], off
	global_load_ushort v14, v[6:7], off offset:-3072
	s_nop 0
	global_load_ushort v150, v[6:7], off
	v_lshl_add_u64 v[4:5], s[62:63], 0, v[106:107]
	global_load_ushort v151, v[4:5], off
	v_lshl_add_u64 v[4:5], s[52:53], 0, v[106:107]
	global_load_ushort v152, v[4:5], off
.LBB0_477:
	ds_read2st64_b32 v[4:5], v8 offset1:32
	s_waitcnt lgkmcnt(0)
	v_add_f32_e32 v4, v122, v4
	v_mul_f32_e32 v4, 0xbfb8aa3b, v4
	v_exp_f32_e32 v4, v4
	s_nop 0
	v_add_f32_e32 v4, 1.0, v4
	v_rcp_f32_e32 v4, v4
	s_nop 0
	v_mul_f32_e32 v4, 0xc1000000, v4
	v_mul_f32_e32 v4, v124, v4
	v_mul_f32_e32 v6, 0x3fb8aa3b, v4
	v_exp_f32_e32 v185, v6
	v_add_f32_e32 v6, v4, v4
	v_cmp_nlt_f32_e32 vcc, s51, v6
	s_and_saveexec_b64 s[36:37], vcc
	s_xor_b64 s[36:37], exec, s[36:37]
	v_fma_f32 v4, -v185, v185, 1.0
	s_andn2_saveexec_b64 s[36:37], s[36:37]
	v_fmamk_f32 v4, v6, 0x3d2aaaab, v222
	v_fma_f32 v4, v6, v4, 0.5
	v_fma_f32 v4, v6, v4, 1.0
	v_mul_f32_e64 v4, v4, -v6
	s_or_b64 exec, exec, s[36:37]
	v_add_f32_e32 v5, v123, v5
	v_mul_f32_e32 v5, 0xbfb8aa3b, v5
	v_exp_f32_e32 v5, v5
	v_sqrt_f32_e32 v4, v4
	v_fma_f32 v6, v76, v108, v84
	v_fmac_f32_e32 v6, v78, v113
	v_add_f32_e32 v5, 1.0, v5
	v_rcp_f32_e32 v5, v5
	v_fmac_f32_e32 v6, v80, v9
	v_fmac_f32_e32 v6, v82, v62
	v_mov_b32_e32 v108, v0
	v_mul_f32_e32 v4, v5, v4
	v_mul_f32_e32 v5, v6, v4
	v_mul_f32_e32 v4, 0x3d372713, v0
	v_mul_f32_e32 v4, v0, v4
	v_fma_f32 v4, v0, v4, v0
	v_mul_f32_e32 v4, 0x3f4c422a, v4
	v_add_f32_e32 v4, v4, v4
	v_mul_f32_e32 v4, 0x3fb8aa3b, v4
	v_exp_f32_e32 v4, v4
	v_pk_mul_f32 v[6:7], v[108:109], v[184:185]
	v_add_f32_e32 v4, 1.0, v4
	v_rcp_f32_e32 v4, v4
	s_nop 0
	v_fma_f32 v4, v4, -2.0, 1.0
	v_add_f32_e32 v4, 1.0, v4
	v_pk_mul_f32 v[6:7], v[6:7], v[4:5]
	v_pk_fma_f32 v[4:5], v[108:109], v[184:185], v[4:5]
	s_nop 0
	v_pk_mul_f32 v[6:7], v[6:7], v[4:5] op_sel:[0,1] op_sel_hi:[1,0]
	s_nop 0
	v_bfe_u32 v0, v6, 16, 1
	v_add3_u32 v0, v6, v0, s25
	v_lshl_add_u64 v[6:7], s[6:7], 0, v[106:107]
	global_store_short_d16_hi v[6:7], v0, off
	ds_read2st64_b32 v[6:7], v8 offset0:1 offset1:33
	s_waitcnt lgkmcnt(0)
	v_add_f32_e32 v0, v122, v6
	v_mul_f32_e32 v0, 0xbfb8aa3b, v0
	v_exp_f32_e32 v0, v0
	s_nop 0
	v_add_f32_e32 v0, 1.0, v0
	v_rcp_f32_e32 v0, v0
	s_nop 0
	v_mul_f32_e32 v0, 0xc1000000, v0
	v_mul_f32_e32 v0, v124, v0
	v_mul_f32_e32 v4, 0x3fb8aa3b, v0
	v_exp_f32_e32 v185, v4
	v_add_f32_e32 v4, v0, v0
	v_cmp_nlt_f32_e32 vcc, s51, v4
	s_and_saveexec_b64 s[36:37], vcc
	s_xor_b64 s[36:37], exec, s[36:37]
	v_fma_f32 v0, -v185, v185, 1.0
	s_andn2_saveexec_b64 s[36:37], s[36:37]
	v_fmamk_f32 v0, v4, 0x3d2aaaab, v222
	v_fma_f32 v0, v4, v0, 0.5
	v_fma_f32 v0, v4, v0, 1.0
	v_mul_f32_e64 v0, v0, -v4
	s_or_b64 exec, exec, s[36:37]
	v_add_f32_e32 v6, v123, v7
	v_mul_f32_e32 v6, 0xbfb8aa3b, v6
	v_exp_f32_e32 v6, v6
	v_sqrt_f32_e32 v0, v0
	v_fma_f32 v4, v76, v113, v84
	v_fmac_f32_e32 v4, v78, v9
	v_add_f32_e32 v6, 1.0, v6
	v_rcp_f32_e32 v6, v6
	v_fmac_f32_e32 v4, v80, v62
	v_fmac_f32_e32 v4, v82, v63
	v_mul_f32_e32 v0, v6, v0
	v_mul_f32_e32 v7, v4, v0
	v_mul_f32_e32 v0, 0x3d372713, v1
	v_mul_f32_e32 v0, v1, v0
	v_fma_f32 v0, v1, v0, v1
	v_mul_f32_e32 v0, 0x3f4c422a, v0
	v_add_f32_e32 v0, v0, v0
	v_mul_f32_e32 v0, 0x3fb8aa3b, v0
	v_exp_f32_e32 v0, v0
	v_mov_b32_e32 v4, v1
	v_add_f32_e32 v0, 1.0, v0
	v_rcp_f32_e32 v0, v0
	s_nop 0
	v_fma_f32 v0, v0, -2.0, 1.0
	v_add_f32_e32 v6, 1.0, v0
	v_pk_mul_f32 v[0:1], v[4:5], v[184:185]
	s_nop 0
	v_pk_mul_f32 v[10:11], v[0:1], v[6:7]
	v_pk_fma_f32 v[0:1], v[4:5], v[184:185], v[6:7]
	s_nop 0
	v_pk_mul_f32 v[4:5], v[10:11], v[0:1] op_sel:[0,1] op_sel_hi:[1,0]
	s_nop 0
	v_bfe_u32 v0, v4, 16, 1
	v_add3_u32 v0, v4, v0, s25
	v_lshl_add_u64 v[4:5], s[70:71], 0, v[106:107]
	global_store_short_d16_hi v[4:5], v0, off
	ds_read2st64_b32 v[4:5], v8 offset0:2 offset1:34
	s_waitcnt lgkmcnt(0)
; __device__ __forceinline__ float sigmoidf_(float x) { return __builtin_amdgcn_rcpf(1.f + __expf(-x)); }
; template <bool FINAL>
; __device__ __forceinline__ void lru_job(const Params& P, int j, int b, int chunk, int h, char* ldsw) {
;     ...
;       for (int q = 0; q < 4; ++q) {
;         const int tt = tg + q;
;         const float xt = xq[q];
;         float xcv = cb + v0 * cw0 + v1 * cw1 + v2 * cw2 + xt * cw3;
;         v0 = v1; v1 = v2; v2 = xt;
;         float rr = sigmoidf_(rbuf[tt * 64 + lane] + ba);
;         float ii = sigmoidf_(ibuf[tt * 64 + lane] + bx);
;         float la = -8.f * rr * sp;
;         float a = __expf(la);
;         const float x2 = 2.f * la;
;         const float om = (x2 > -0.03f) ? -x2 * (1.f + x2 * (0.5f + x2 * (0.16666667f + x2 * 0.041666667f))) : 1.f - a * a;
;         float bc = __builtin_amdgcn_sqrtf(om);
;         hst = a * hst + bc * ii * xcv;
;         if (FINAL) {
;           Y[(rowb + tt) * 1024 + ch] = f2bf(hst * gelu_tanh(yq[q]));
;         } else {
;           Ap *= a;
;         }
;       }
; #pragma unroll
;       for (int q = 0; q < 4; ++q) { xq[q] = xqn[q]; yq[q] = yqn[q]; }
	v_add_f32_e32 v0, v122, v4
	v_mul_f32_e32 v0, 0xbfb8aa3b, v0
	v_exp_f32_e32 v0, v0
	s_nop 0
	v_add_f32_e32 v0, 1.0, v0
	v_rcp_f32_e32 v0, v0
	s_nop 0
	v_mul_f32_e32 v0, 0xc1000000, v0
	v_mul_f32_e32 v0, v124, v0
	v_mul_f32_e32 v4, 0x3fb8aa3b, v0
	v_exp_f32_e32 v185, v4
	v_add_f32_e32 v4, v0, v0
	v_cmp_nlt_f32_e32 vcc, s51, v4
	s_and_saveexec_b64 s[36:37], vcc
	s_xor_b64 s[36:37], exec, s[36:37]
	v_fma_f32 v0, -v185, v185, 1.0
	s_andn2_saveexec_b64 s[36:37], s[36:37]
	v_fmamk_f32 v0, v4, 0x3d2aaaab, v222
	v_fma_f32 v0, v4, v0, 0.5
	v_fma_f32 v0, v4, v0, 1.0
	v_mul_f32_e64 v0, v0, -v4
	s_or_b64 exec, exec, s[36:37]
	v_add_f32_e32 v5, v123, v5
	v_mul_f32_e32 v5, 0xbfb8aa3b, v5
	v_exp_f32_e32 v5, v5
	v_sqrt_f32_e32 v0, v0
	v_fma_f32 v4, v76, v9, v84
	v_fmac_f32_e32 v4, v78, v62
	v_add_f32_e32 v5, 1.0, v5
	v_rcp_f32_e32 v5, v5
	v_fmac_f32_e32 v4, v80, v63
	v_fmac_f32_e32 v4, v82, v64
	v_mul_f32_e32 v0, v5, v0
	v_mul_f32_e32 v5, v4, v0
	v_mul_f32_e32 v0, 0x3d372713, v2
	v_mul_f32_e32 v0, v2, v0
	v_fma_f32 v0, v2, v0, v2
	v_mul_f32_e32 v0, 0x3f4c422a, v0
	v_add_f32_e32 v0, v0, v0
	v_mul_f32_e32 v0, 0x3fb8aa3b, v0
	v_exp_f32_e32 v0, v0
	s_nop 0
	v_add_f32_e32 v0, 1.0, v0
	v_rcp_f32_e32 v0, v0
	s_nop 0
	v_fma_f32 v0, v0, -2.0, 1.0
	v_add_f32_e32 v4, 1.0, v0
	v_mov_b32_e32 v0, v2
	v_pk_mul_f32 v[6:7], v[0:1], v[184:185]
	s_nop 0
	v_pk_mul_f32 v[6:7], v[6:7], v[4:5]
	v_pk_fma_f32 v[4:5], v[0:1], v[184:185], v[4:5]
	s_nop 0
	v_pk_mul_f32 v[0:1], v[6:7], v[4:5] op_sel:[0,1] op_sel_hi:[1,0]
	ds_read2st64_b32 v[6:7], v8 offset0:3 offset1:35
	v_bfe_u32 v1, v0, 16, 1
	v_add3_u32 v2, v0, v1, s25
	v_lshl_add_u64 v[0:1], s[68:69], 0, v[106:107]
	global_store_short_d16_hi v[0:1], v2, off
	s_waitcnt lgkmcnt(0)
	v_add_f32_e32 v2, v122, v6
	v_mul_f32_e32 v2, 0xbfb8aa3b, v2
	v_exp_f32_e32 v2, v2
	s_nop 0
	v_add_f32_e32 v2, 1.0, v2
	v_rcp_f32_e32 v2, v2
	s_nop 0
	v_mul_f32_e32 v2, 0xc1000000, v2
	v_mul_f32_e32 v2, v124, v2
	v_mul_f32_e32 v4, 0x3fb8aa3b, v2
	v_exp_f32_e32 v185, v4
	v_add_f32_e32 v4, v2, v2
	v_cmp_nlt_f32_e32 vcc, s51, v4
	s_and_saveexec_b64 s[36:37], vcc
	s_xor_b64 s[36:37], exec, s[36:37]
	v_fma_f32 v2, -v185, v185, 1.0
	s_andn2_saveexec_b64 s[36:37], s[36:37]
	v_fmamk_f32 v2, v4, 0x3d2aaaab, v222
	v_fma_f32 v2, v4, v2, 0.5
	v_fma_f32 v2, v4, v2, 1.0
	v_mul_f32_e64 v2, v2, -v4
	s_or_b64 exec, exec, s[36:37]
	v_add_f32_e32 v4, v123, v7
	v_mul_f32_e32 v7, 0x3d372713, v3
	v_mul_f32_e32 v7, v3, v7
	v_mov_b32_e32 v9, v3
	v_fmac_f32_e32 v9, v9, v7
	v_mul_f32_e32 v7, 0x3f4c422a, v9
	v_add_f32_e32 v7, v7, v7
	s_add_u32 s8, s8, 0x3000
	v_mul_f32_e32 v4, 0xbfb8aa3b, v4
	v_mul_f32_e32 v7, 0x3fb8aa3b, v7
	s_addc_u32 s9, s9, 0
	v_exp_f32_e32 v4, v4
	v_exp_f32_e32 v7, v7
	s_add_u32 s10, s10, 0x3000
	s_addc_u32 s11, s11, 0
	s_add_u32 s52, s52, 0x3000
	s_addc_u32 s53, s53, 0
	v_add_f32_e32 v4, 1.0, v4
	v_add_f32_e32 v7, 1.0, v7
	s_add_u32 s54, s54, 0x3000
	v_rcp_f32_e32 v4, v4
	v_sqrt_f32_e32 v2, v2
	v_rcp_f32_e32 v7, v7
	s_addc_u32 s55, s55, 0
	s_add_u32 s60, s60, 0x3000
	s_addc_u32 s61, s61, 0
	v_fma_f32 v6, v76, v62, v84
	s_add_u32 s62, s62, 0x3000
	v_fmac_f32_e32 v6, v78, v63
	v_mul_f32_e32 v2, v4, v2
	v_fma_f32 v4, v7, -2.0, 1.0
	s_addc_u32 s63, s63, 0
	v_fmac_f32_e32 v6, v80, v64
	v_add_f32_e32 v7, 1.0, v4
	v_mov_b32_e32 v4, v3
	s_add_u32 s68, s68, 0x2000
	v_fmac_f32_e32 v6, v82, v65
	v_pk_mul_f32 v[108:109], v[4:5], v[184:185]
	s_addc_u32 s69, s69, 0
	v_mul_f32_e32 v3, v108, v7
	v_fmac_f32_e32 v109, v6, v2
	s_add_u32 s70, s70, 0x2000
	v_mul_f32_e32 v2, v3, v109
	s_addc_u32 s71, s71, 0
	v_bfe_u32 v3, v2, 16, 1
	s_add_u32 s6, s6, 0x2000
	v_add3_u32 v2, v2, v3, s25
	v_mov_b32_e32 v108, v63
	v_mov_b32_e32 v113, v64
	v_add_u32_e32 v8, 0x400, v8
	s_addc_u32 s7, s7, 0
	s_and_b64 vcc, exec, s[72:73]
	global_store_short_d16_hi v[0:1], v2, off offset:2048
	s_cbranch_vccnz .LBB0_473
	v_mov_b32_e32 v9, v65
	s_waitcnt vmcnt(4)
	v_lshlrev_b32_e32 v66, 16, v153
	v_lshlrev_b32_e32 v70, 16, v154
	v_lshlrev_b32_e32 v67, 16, v12
	v_lshlrev_b32_e32 v71, 16, v14
	v_lshlrev_b32_e32 v68, 16, v13
	v_lshlrev_b32_e32 v72, 16, v150
	v_lshlrev_b32_e32 v69, 16, v151
	v_lshlrev_b32_e32 v73, 16, v152
	v_mov_b64_e32 v[62:63], v[66:67]
	v_mov_b64_e32 v[0:1], v[70:71]
	v_mov_b64_e32 v[64:65], v[68:69]
	v_mov_b64_e32 v[2:3], v[72:73]
	s_branch .LBB0_475

; __device__ __forceinline__ float bf2f(u16 h) { return __uint_as_float(((uint32_t)h) << 16); }
; __device__ __forceinline__ float sigmoidf_(float x) { return __builtin_amdgcn_rcpf(1.f + __expf(-x)); }
; template <bool FINAL>
; __device__ __forceinline__ void lru_job(const Params& P, int j, int b, int chunk, int h, char* ldsw) {
;     ...
;     for (int tg = 0; tg < 32; tg += 4) {
;       if (tg + 4 < 32) {
; #pragma unroll
;         for (int q = 0; q < 4; ++q) {
;           xqn[q] = bf2f(xs[(size_t)(tg + 4 + q) * 1536]);
;           yqn[q] = FINAL ? bf2f(Z[(rowb + tg + 4 + q) * 1536 + 512 + ch]) : 0.f;
;         }
;       }
; #pragma unroll
;       for (int q = 0; q < 4; ++q) {
;         const int tt = tg + q;
;         const float xt = xq[q];
;         float xcv = cb + v0 * cw0 + v1 * cw1 + v2 * cw2 + xt * cw3;
;         v0 = v1; v1 = v2; v2 = xt;
;         float rr = sigmoidf_(rbuf[tt * 64 + lane] + ba);
;         float ii = sigmoidf_(ibuf[tt * 64 + lane] + bx);
;         float la = -8.f * rr * sp;
;         float a = __expf(la);
;         const float x2 = 2.f * la;
;         const float om = (x2 > -0.03f) ? -x2 * (1.f + x2 * (0.5f + x2 * (0.16666667f + x2 * 0.041666667f))) : 1.f - a * a;
;         float bc = __builtin_amdgcn_sqrtf(om);
;         hst = a * hst + bc * ii * xcv;
;         if (FINAL) {
;           Y[(rowb + tt) * 1024 + ch] = f2bf(hst * gelu_tanh(yq[q]));
;         } else {
;           Ap *= a;
;         }
;       }
; #pragma unroll
;       for (int q = 0; q < 4; ++q) { xq[q] = xqn[q]; yq[q] = yqn[q]; }
.LBB0_541:
	s_add_i32 s14, s14, 4
	s_cmp_gt_u32 s14, 27
	s_cselect_b64 s[0:1], -1, 0
	s_and_b64 vcc, exec, s[0:1]
	s_cbranch_vccnz .LBB0_543
	v_add_co_u32_e32 v2, vcc, 0xffffe000, v0
	s_nop 1
	v_addc_co_u32_e32 v3, vcc, -1, v1, vcc
	v_add_co_u32_e32 v4, vcc, 0xfffff000, v0
	s_nop 1
	v_addc_co_u32_e32 v5, vcc, -1, v1, vcc
	global_load_ushort v198, v[2:3], off offset:-1024
	s_nop 0
	global_load_ushort v199, v[4:5], off offset:-2048
	s_nop 0
	global_load_ushort v200, v[0:1], off offset:-3072
	global_load_ushort v201, v[0:1], off
.LBB0_543:
	ds_read2st64_b32 v[2:3], v10 offset1:32
	s_waitcnt lgkmcnt(0)
	v_add_f32_e32 v2, v174, v2
	v_mul_f32_e32 v2, 0xbfb8aa3b, v2
	v_exp_f32_e32 v2, v2
	s_nop 0
	v_add_f32_e32 v2, 1.0, v2
	v_rcp_f32_e32 v2, v2
	s_nop 0
	v_mul_f32_e32 v2, 0xc1000000, v2
	v_mul_f32_e32 v2, v176, v2
	v_mul_f32_e32 v4, 0x3fb8aa3b, v2
	v_exp_f32_e32 v12, v4
	v_add_f32_e32 v2, v2, v2
	v_cmp_nlt_f32_e32 vcc, s51, v2
	s_and_saveexec_b64 s[6:7], vcc
	s_xor_b64 s[6:7], exec, s[6:7]
	v_fma_f32 v14, -v12, v12, 1.0
	s_andn2_saveexec_b64 s[6:7], s[6:7]
	v_fmamk_f32 v4, v2, 0x3d2aaaab, v222
	v_fma_f32 v4, v2, v4, 0.5
	v_fma_f32 v4, v2, v4, 1.0
	v_mul_f32_e64 v14, v4, -v2
	s_or_b64 exec, exec, s[6:7]
	ds_read2st64_b32 v[4:5], v10 offset0:1 offset1:33
	s_waitcnt lgkmcnt(0)
	v_add_f32_e32 v2, v174, v4
	v_mul_f32_e32 v2, 0xbfb8aa3b, v2
	v_exp_f32_e32 v2, v2
	s_nop 0
	v_add_f32_e32 v2, 1.0, v2
	v_rcp_f32_e32 v2, v2
	s_nop 0
	v_mul_f32_e32 v2, 0xc1000000, v2
	v_mul_f32_e32 v2, v176, v2
	v_mul_f32_e32 v4, 0x3fb8aa3b, v2
	v_exp_f32_e32 v13, v4
	v_add_f32_e32 v2, v2, v2
	v_cmp_nlt_f32_e32 vcc, s51, v2
	s_and_saveexec_b64 s[6:7], vcc
	s_xor_b64 s[6:7], exec, s[6:7]
	v_fma_f32 v15, -v13, v13, 1.0
	s_andn2_saveexec_b64 s[6:7], s[6:7]
	v_fmamk_f32 v4, v2, 0x3d2aaaab, v222
	v_fma_f32 v4, v2, v4, 0.5
	v_fma_f32 v4, v2, v4, 1.0
	v_mul_f32_e64 v15, v4, -v2
	s_or_b64 exec, exec, s[6:7]
	ds_read2st64_b32 v[6:7], v10 offset0:2 offset1:34
	s_waitcnt lgkmcnt(0)
	v_add_f32_e32 v2, v174, v6
	v_mul_f32_e32 v2, 0xbfb8aa3b, v2
	v_exp_f32_e32 v2, v2
	s_nop 0
	v_add_f32_e32 v2, 1.0, v2
	v_rcp_f32_e32 v2, v2
	s_nop 0
	v_mul_f32_e32 v2, 0xc1000000, v2
	v_mul_f32_e32 v4, v176, v2
	v_mul_f32_e32 v2, 0x3fb8aa3b, v4
	v_exp_f32_e32 v2, v2
	v_add_f32_e32 v4, v4, v4
	v_cmp_nlt_f32_e32 vcc, s51, v4
	s_and_saveexec_b64 s[6:7], vcc
	s_xor_b64 s[6:7], exec, s[6:7]
	v_fma_f32 v6, -v2, v2, 1.0
	s_andn2_saveexec_b64 s[6:7], s[6:7]
	v_fmamk_f32 v6, v4, 0x3d2aaaab, v222
	v_fma_f32 v6, v4, v6, 0.5
	v_fma_f32 v6, v4, v6, 1.0
	v_mul_f32_e64 v6, v6, -v4
	s_or_b64 exec, exec, s[6:7]
	ds_read2st64_b32 v[8:9], v10 offset0:3 offset1:35
	s_waitcnt lgkmcnt(0)
	v_add_f32_e32 v4, v174, v8
	v_mul_f32_e32 v4, 0xbfb8aa3b, v4
	v_exp_f32_e32 v4, v4
	s_nop 0
	v_add_f32_e32 v4, 1.0, v4
	v_rcp_f32_e32 v4, v4
	s_nop 0
	v_mul_f32_e32 v4, 0xc1000000, v4
	v_mul_f32_e32 v8, v176, v4
	v_mul_f32_e32 v4, 0x3fb8aa3b, v8
	v_exp_f32_e32 v4, v4
	v_add_f32_e32 v16, v8, v8
	v_cmp_nlt_f32_e32 vcc, s51, v16
	s_and_saveexec_b64 s[6:7], vcc
	s_xor_b64 s[6:7], exec, s[6:7]
	v_fma_f32 v8, -v4, v4, 1.0
	s_andn2_saveexec_b64 s[6:7], s[6:7]
	v_fmamk_f32 v8, v16, 0x3d2aaaab, v222
	v_fma_f32 v8, v16, v8, 0.5
	v_fma_f32 v8, v16, v8, 1.0
	v_mul_f32_e64 v8, v8, -v16
	s_or_b64 exec, exec, s[6:7]
	v_add_f32_e32 v3, v175, v3
	v_mul_f32_e32 v3, 0xbfb8aa3b, v3
	v_exp_f32_e32 v3, v3
	v_add_f32_e32 v5, v175, v5
	v_mul_f32_e32 v5, 0xbfb8aa3b, v5
	v_exp_f32_e32 v5, v5
	v_add_f32_e32 v3, 1.0, v3
	v_sqrt_f32_e32 v14, v14
	v_rcp_f32_e32 v3, v3
	v_add_f32_e32 v5, 1.0, v5
	v_fma_f32 v16, v142, v114, v150
	v_rcp_f32_e32 v5, v5
	v_sqrt_f32_e32 v15, v15
	v_fmac_f32_e32 v16, v144, v113
	v_mul_f32_e32 v3, v3, v14
	v_fma_f32 v14, v142, v113, v150
	v_fmac_f32_e32 v16, v146, v11
	v_fmac_f32_e32 v14, v144, v11
	v_fmac_f32_e32 v16, v149, v132
	v_fmac_f32_e32 v14, v146, v132
	v_mul_f32_e32 v3, v16, v3
	v_fmac_f32_e32 v14, v149, v133
	v_mul_f32_e32 v5, v5, v15
	v_fmac_f32_e32 v3, v155, v12
	v_mul_f32_e32 v148, v14, v5
	v_fmac_f32_e32 v148, v3, v13
	v_add_f32_e32 v3, v175, v7
	v_mul_f32_e32 v3, 0xbfb8aa3b, v3
	v_exp_f32_e32 v3, v3
	v_sqrt_f32_e32 v6, v6
	v_fma_f32 v7, v142, v11, v150
	v_fmac_f32_e32 v7, v144, v132
	v_add_f32_e32 v3, 1.0, v3
	v_rcp_f32_e32 v3, v3
	v_fmac_f32_e32 v7, v146, v133
	v_fmac_f32_e32 v7, v149, v134
	v_mul_f32_e32 v12, v154, v12
	v_mul_f32_e32 v3, v3, v6
	v_mul_f32_e32 v6, v7, v3
	v_add_f32_e32 v3, v175, v9
	v_mul_f32_e32 v3, 0xbfb8aa3b, v3
	v_exp_f32_e32 v3, v3
	v_mul_f32_e32 v5, v12, v13
	v_mul_f32_e32 v9, v5, v2
	v_sqrt_f32_e32 v8, v8
	v_add_f32_e32 v3, 1.0, v3
	v_rcp_f32_e32 v5, v3
	v_fma_f32 v7, v142, v132, v150
	v_fmac_f32_e32 v7, v144, v133
	v_fmac_f32_e32 v7, v146, v134
	v_mov_b32_e32 v3, v135
	v_pk_fma_f32 v[2:3], v[148:149], v[2:3], v[6:7]
	v_mul_f32_e32 v5, v5, v8
	v_pk_mul_f32 v[2:3], v[2:3], v[4:5]
	s_mov_b64 s[6:7], 0x3000
	v_mov_b32_e32 v114, v133
	v_mov_b32_e32 v113, v134
	v_add_f32_e32 v155, v2, v3
	v_mul_f32_e32 v154, v9, v4
	v_lshl_add_u64 v[0:1], v[0:1], 0, s[6:7]
	v_add_u32_e32 v10, 0x400, v10
	s_and_b64 vcc, exec, s[0:1]
	s_cbranch_vccnz .LBB0_539
	v_mov_b32_e32 v11, v135
	s_waitcnt vmcnt(0)
	v_lshlrev_b32_e32 v136, 16, v198
	v_lshlrev_b32_e32 v137, 16, v199
	v_lshlrev_b32_e32 v138, 16, v200
	v_lshlrev_b32_e32 v139, 16, v201
	v_mov_b64_e32 v[132:133], v[136:137]
	v_mov_b64_e32 v[134:135], v[138:139]
	s_branch .LBB0_541
